# same as previous but P6/P8 load-side lane transposes removed (store-side coalescing kept)
# baseline (speedup 1.0000x reference)
.LBB0_1373:
	v_and_b32_e32 v236, 48, v144
	v_mul_u32_u24_e32 v232, 3, v236
	v_sub_u32_e32 v232, 0, v232
	v_ashrrev_i32_e32 v233, 31, v232
	v_sub_u32_e32 v236, 0, v236
	v_ashrrev_i32_e32 v237, 31, v236
	v_lshl_add_u32 v140, s30, 8, v142
	v_ashrrev_i32_e32 v141, 31, v140
	v_readlane_b32 s60, v240, 5
	v_lshl_or_b32 v138, s8, 8, v144
	v_lshlrev_b64 v[150:151], 12, v[140:141]
	v_readlane_b32 s61, v240, 6
	v_ashrrev_i32_e32 v139, 31, v138
	v_xor_b32_e32 v149, 16, v148
	v_lshl_add_u64 v[150:151], s[60:61], 0, v[150:151]
	v_lshl_add_u64 v[150:151], v[138:139], 2, v[150:151]
	global_load_dwordx4 v[152:155], v[150:151], off
	global_load_dwordx4 v[156:159], v[150:151], off offset:16
	global_load_dwordx4 v[160:163], v[150:151], off offset:32
	global_load_dwordx4 v[164:167], v[150:151], off offset:48
	v_and_b32_e32 v150, 64, v148
	v_add_u32_e32 v150, 64, v150
	v_cmp_lt_i32_e32 vcc, v149, v150
	v_xor_b32_e32 v151, 32, v148
	v_lshlrev_b64 v[168:169], 11, v[140:141]
	v_cndmask_b32_e32 v149, v148, v149, vcc
	v_cmp_lt_i32_e32 vcc, v151, v150
	v_lshlrev_b32_e32 v150, 2, v149
	s_lshl_b32 s30, s8, 2
	v_cndmask_b32_e32 v151, v148, v151, vcc
	v_lshlrev_b32_e32 v149, 2, v151
	v_lshl_add_u64 v[168:169], s[12:13], 0, v[168:169]
	s_ashr_i32 s31, s30, 31
	v_lshl_add_u64 v[168:169], v[138:139], 1, v[168:169]
	v_readlane_b32 s62, v240, 7
	v_readlane_b32 s63, v240, 8
	s_waitcnt vmcnt(0)
	v_pk_add_f32 v[120:121], v[120:121], v[152:153]
	v_pk_add_f32 v[122:123], v[122:123], v[154:155]
	v_pk_add_f32 v[152:153], v[118:119], v[162:163]
	v_pk_add_f32 v[118:119], v[116:117], v[160:161]
	v_pk_mul_f32 v[116:117], v[120:121], v[120:121]
	v_pk_add_f32 v[124:125], v[124:125], v[156:157]
	v_pk_add_f32 v[154:155], v[114:115], v[166:167]
	v_pk_add_f32 v[156:157], v[112:113], v[164:165]
	v_pk_mul_f32 v[112:113], v[122:123], v[122:123]
	v_add_f32_e32 v115, v116, v117
	v_add_f32_e32 v112, v112, v115
	v_pk_mul_f32 v[160:161], v[124:125], v[124:125]
	v_add_f32_e32 v112, v113, v112
	v_pk_add_f32 v[126:127], v[126:127], v[158:159]
	v_add_f32_e32 v112, v160, v112
	v_pk_mul_f32 v[158:159], v[126:127], v[126:127]
	v_add_f32_e32 v112, v161, v112
	v_add_f32_e32 v112, v158, v112
	v_pk_mul_f32 v[164:165], v[118:119], v[118:119]
	v_add_f32_e32 v112, v159, v112
	v_add_f32_e32 v112, v164, v112
	v_pk_mul_f32 v[162:163], v[152:153], v[152:153]
	v_add_f32_e32 v112, v165, v112
	v_add_f32_e32 v112, v162, v112
	v_pk_mul_f32 v[170:171], v[156:157], v[156:157]
	v_add_f32_e32 v112, v163, v112
	v_add_f32_e32 v112, v170, v112
	v_pk_mul_f32 v[166:167], v[154:155], v[154:155]
	v_add_f32_e32 v112, v171, v112
	v_add_f32_e32 v112, v166, v112
	v_add_f32_e32 v112, v167, v112
	ds_bpermute_b32 v113, v150, v112
	v_cvt_pk_bf16_f32 v114, v120, v121
	v_cvt_pk_bf16_f32 v115, v122, v123
	v_cvt_pk_bf16_f32 v116, v124, v125
	v_cvt_pk_bf16_f32 v117, v126, v127
	s_waitcnt lgkmcnt(0)
	v_add_f32_e32 v112, v112, v113
	ds_bpermute_b32 v113, v149, v112
	v_cvt_pk_bf16_f32 v118, v118, v119
	v_cvt_pk_bf16_f32 v119, v152, v153
	v_cvt_pk_bf16_f32 v120, v156, v157
	v_cvt_pk_bf16_f32 v121, v154, v155
	s_nop 1
	v_permlane16_swap_b32_e32 v114, v118
	v_permlane16_swap_b32_e32 v115, v119
	v_permlane16_swap_b32_e32 v116, v120
	v_permlane16_swap_b32_e32 v117, v121
	v_permlane32_swap_b32_e32 v114, v118
	v_permlane32_swap_b32_e32 v115, v119
	v_permlane32_swap_b32_e32 v116, v120
	v_permlane32_swap_b32_e32 v117, v121
	v_lshl_add_u64 v[238:239], v[168:169], 0, v[236:237]
	global_store_dwordx4 v[238:239], v[114:117], off
	global_store_dwordx4 v[238:239], v[118:121], off offset:64
	s_and_saveexec_b64 s[4:5], s[6:7]
	s_cbranch_execz .LBB0_1375
	v_lshlrev_b64 v[114:115], 6, v[140:141]
	v_lshl_add_u64 v[114:115], s[14:15], 0, v[114:115]
	v_lshl_add_u64 v[114:115], s[30:31], 2, v[114:115]
	s_lshl_b32 s8, s46, 2
	v_lshl_add_u64 v[114:115], v[114:115], 0, s[8:9]
	s_waitcnt lgkmcnt(0)
	v_add_f32_e32 v112, v112, v113
	global_store_dword v[114:115], v112, off
.LBB0_1375:
	s_or_b64 exec, exec, s[4:5]
	v_or_b32_e32 v112, 16, v140
	s_waitcnt lgkmcnt(0)
	v_ashrrev_i32_e32 v113, 31, v112
	v_readlane_b32 s60, v240, 5
	v_lshlrev_b64 v[114:115], 12, v[112:113]
	v_readlane_b32 s61, v240, 6
	v_readlane_b32 s62, v240, 7
	v_readlane_b32 s63, v240, 8
	v_lshl_add_u64 v[114:115], s[60:61], 0, v[114:115]
	v_lshl_add_u64 v[126:127], v[138:139], 2, v[114:115]
	global_load_dwordx4 v[114:117], v[126:127], off
	global_load_dwordx4 v[118:121], v[126:127], off offset:16
	global_load_dwordx4 v[122:125], v[126:127], off offset:32
	global_load_dwordx4 v[152:155], v[126:127], off offset:48
	v_lshlrev_b64 v[126:127], 11, v[112:113]
	v_lshl_add_u64 v[126:127], s[12:13], 0, v[126:127]
	v_lshl_add_u64 v[126:127], v[138:139], 1, v[126:127]
	s_waitcnt vmcnt(3)
	v_pk_add_f32 v[108:109], v[108:109], v[114:115]
	v_pk_add_f32 v[110:111], v[110:111], v[116:117]
	s_waitcnt vmcnt(1)
	v_pk_add_f32 v[114:115], v[102:103], v[124:125]
	v_pk_add_f32 v[102:103], v[100:101], v[122:123]
	v_pk_mul_f32 v[100:101], v[108:109], v[108:109]
	v_pk_add_f32 v[104:105], v[104:105], v[118:119]
	s_waitcnt vmcnt(0)
	v_pk_add_f32 v[116:117], v[98:99], v[154:155]
	v_pk_add_f32 v[118:119], v[96:97], v[152:153]
	v_pk_mul_f32 v[96:97], v[110:111], v[110:111]
	v_add_f32_e32 v99, v100, v101
	v_add_f32_e32 v96, v96, v99
	v_pk_mul_f32 v[122:123], v[104:105], v[104:105]
	v_add_f32_e32 v96, v97, v96
	v_pk_add_f32 v[106:107], v[106:107], v[120:121]
	v_add_f32_e32 v96, v122, v96
	v_pk_mul_f32 v[120:121], v[106:107], v[106:107]
	v_add_f32_e32 v96, v123, v96
	v_add_f32_e32 v96, v120, v96
	v_pk_mul_f32 v[152:153], v[102:103], v[102:103]
	v_add_f32_e32 v96, v121, v96
	v_add_f32_e32 v96, v152, v96
	v_pk_mul_f32 v[124:125], v[114:115], v[114:115]
	v_add_f32_e32 v96, v153, v96
	v_add_f32_e32 v96, v124, v96
	v_pk_mul_f32 v[156:157], v[118:119], v[118:119]
	v_add_f32_e32 v96, v125, v96
	v_add_f32_e32 v96, v156, v96
	v_pk_mul_f32 v[154:155], v[116:117], v[116:117]
	v_add_f32_e32 v96, v157, v96
	v_add_f32_e32 v96, v154, v96
	v_add_f32_e32 v96, v155, v96
	ds_bpermute_b32 v97, v150, v96
	v_cvt_pk_bf16_f32 v98, v108, v109
	v_cvt_pk_bf16_f32 v99, v110, v111
	v_cvt_pk_bf16_f32 v100, v104, v105
	v_cvt_pk_bf16_f32 v101, v106, v107
	s_waitcnt lgkmcnt(0)
	v_add_f32_e32 v96, v96, v97
	ds_bpermute_b32 v97, v149, v96
	v_cvt_pk_bf16_f32 v102, v102, v103
	v_cvt_pk_bf16_f32 v103, v114, v115
	v_cvt_pk_bf16_f32 v104, v118, v119
	v_cvt_pk_bf16_f32 v105, v116, v117
	s_nop 1
	v_permlane16_swap_b32_e32 v98, v102
	v_permlane16_swap_b32_e32 v99, v103
	v_permlane16_swap_b32_e32 v100, v104
	v_permlane16_swap_b32_e32 v101, v105
	v_permlane32_swap_b32_e32 v98, v102
	v_permlane32_swap_b32_e32 v99, v103
	v_permlane32_swap_b32_e32 v100, v104
	v_permlane32_swap_b32_e32 v101, v105
	v_lshl_add_u64 v[238:239], v[126:127], 0, v[236:237]
	global_store_dwordx4 v[238:239], v[98:101], off
	global_store_dwordx4 v[238:239], v[102:105], off offset:64
	s_and_saveexec_b64 s[4:5], s[6:7]
	s_cbranch_execz .LBB0_1377
	v_lshlrev_b64 v[98:99], 6, v[112:113]
	v_lshl_add_u64 v[98:99], s[14:15], 0, v[98:99]
	v_lshl_add_u64 v[98:99], s[30:31], 2, v[98:99]
	s_lshl_b32 s8, s46, 2
	v_lshl_add_u64 v[98:99], v[98:99], 0, s[8:9]
	s_waitcnt lgkmcnt(0)
	v_add_f32_e32 v96, v96, v97
	global_store_dword v[98:99], v96, off
.LBB0_1377:
	s_or_b64 exec, exec, s[4:5]
	v_or_b32_e32 v96, 32, v140
	s_waitcnt lgkmcnt(0)
	v_ashrrev_i32_e32 v97, 31, v96
	v_readlane_b32 s60, v240, 5
	v_lshlrev_b64 v[98:99], 12, v[96:97]
	v_readlane_b32 s61, v240, 6
	v_lshlrev_b64 v[114:115], 11, v[96:97]
	v_lshl_add_u64 v[114:115], s[12:13], 0, v[114:115]
	v_lshl_add_u64 v[98:99], s[60:61], 0, v[98:99]
	v_lshl_add_u64 v[110:111], v[138:139], 2, v[98:99]
	global_load_dwordx4 v[98:101], v[110:111], off
	global_load_dwordx4 v[102:105], v[110:111], off offset:16
	global_load_dwordx4 v[106:109], v[110:111], off offset:32
	s_nop 0
	global_load_dwordx4 v[110:113], v[110:111], off offset:48
	v_lshl_add_u64 v[114:115], v[138:139], 1, v[114:115]
	v_readlane_b32 s62, v240, 7
	v_readlane_b32 s63, v240, 8
	s_waitcnt vmcnt(3)
	v_pk_add_f32 v[92:93], v[92:93], v[98:99]
	v_pk_add_f32 v[94:95], v[94:95], v[100:101]
	s_waitcnt vmcnt(1)
	v_pk_add_f32 v[98:99], v[86:87], v[108:109]
	v_pk_add_f32 v[86:87], v[84:85], v[106:107]
	v_pk_mul_f32 v[84:85], v[92:93], v[92:93]
	v_pk_add_f32 v[88:89], v[88:89], v[102:103]
	s_waitcnt vmcnt(0)
	v_pk_add_f32 v[100:101], v[82:83], v[112:113]
	v_pk_add_f32 v[102:103], v[80:81], v[110:111]
	v_pk_mul_f32 v[80:81], v[94:95], v[94:95]
	v_add_f32_e32 v83, v84, v85
	v_add_f32_e32 v80, v80, v83
	v_pk_mul_f32 v[106:107], v[88:89], v[88:89]
	v_add_f32_e32 v80, v81, v80
	v_pk_add_f32 v[90:91], v[90:91], v[104:105]
	v_add_f32_e32 v80, v106, v80
	v_pk_mul_f32 v[104:105], v[90:91], v[90:91]
	v_add_f32_e32 v80, v107, v80
	v_add_f32_e32 v80, v104, v80
	v_pk_mul_f32 v[110:111], v[86:87], v[86:87]
	v_add_f32_e32 v80, v105, v80
	v_add_f32_e32 v80, v110, v80
	v_pk_mul_f32 v[108:109], v[98:99], v[98:99]
	v_add_f32_e32 v80, v111, v80
	v_add_f32_e32 v80, v108, v80
	v_pk_mul_f32 v[116:117], v[102:103], v[102:103]
	v_add_f32_e32 v80, v109, v80
	v_add_f32_e32 v80, v116, v80
	v_pk_mul_f32 v[112:113], v[100:101], v[100:101]
	v_add_f32_e32 v80, v117, v80
	v_add_f32_e32 v80, v112, v80
	v_add_f32_e32 v80, v113, v80
	ds_bpermute_b32 v81, v150, v80
	v_cvt_pk_bf16_f32 v82, v92, v93
	v_cvt_pk_bf16_f32 v83, v94, v95
	v_cvt_pk_bf16_f32 v84, v88, v89
	v_cvt_pk_bf16_f32 v85, v90, v91
	s_waitcnt lgkmcnt(0)
	v_add_f32_e32 v80, v80, v81
	ds_bpermute_b32 v81, v149, v80
	v_cvt_pk_bf16_f32 v86, v86, v87
	v_cvt_pk_bf16_f32 v87, v98, v99
	v_cvt_pk_bf16_f32 v88, v102, v103
	v_cvt_pk_bf16_f32 v89, v100, v101
	s_nop 1
	v_permlane16_swap_b32_e32 v82, v86
	v_permlane16_swap_b32_e32 v83, v87
	v_permlane16_swap_b32_e32 v84, v88
	v_permlane16_swap_b32_e32 v85, v89
	v_permlane32_swap_b32_e32 v82, v86
	v_permlane32_swap_b32_e32 v83, v87
	v_permlane32_swap_b32_e32 v84, v88
	v_permlane32_swap_b32_e32 v85, v89
	v_lshl_add_u64 v[238:239], v[114:115], 0, v[236:237]
	global_store_dwordx4 v[238:239], v[82:85], off
	global_store_dwordx4 v[238:239], v[86:89], off offset:64
	s_and_saveexec_b64 s[4:5], s[6:7]
	s_cbranch_execz .LBB0_1379
	v_lshlrev_b64 v[82:83], 6, v[96:97]
	v_lshl_add_u64 v[82:83], s[14:15], 0, v[82:83]
	v_lshl_add_u64 v[82:83], s[30:31], 2, v[82:83]
	s_lshl_b32 s8, s46, 2
	v_lshl_add_u64 v[82:83], v[82:83], 0, s[8:9]
	s_waitcnt lgkmcnt(0)
	v_add_f32_e32 v80, v80, v81
	global_store_dword v[82:83], v80, off
.LBB0_1379:
	s_or_b64 exec, exec, s[4:5]
	v_or_b32_e32 v80, 48, v140
	s_waitcnt lgkmcnt(0)
	v_ashrrev_i32_e32 v81, 31, v80
	v_readlane_b32 s60, v240, 5
	v_lshlrev_b64 v[82:83], 12, v[80:81]
	v_readlane_b32 s61, v240, 6
	v_lshlrev_b64 v[98:99], 11, v[80:81]
	v_lshl_add_u64 v[98:99], s[12:13], 0, v[98:99]
	v_lshl_add_u64 v[82:83], s[60:61], 0, v[82:83]
	v_lshl_add_u64 v[94:95], v[138:139], 2, v[82:83]
	global_load_dwordx4 v[82:85], v[94:95], off
	global_load_dwordx4 v[86:89], v[94:95], off offset:16
	global_load_dwordx4 v[90:93], v[94:95], off offset:32
	s_nop 0
	global_load_dwordx4 v[94:97], v[94:95], off offset:48
	v_lshl_add_u64 v[98:99], v[138:139], 1, v[98:99]
	v_readlane_b32 s62, v240, 7
	v_readlane_b32 s63, v240, 8
	s_waitcnt vmcnt(3)
	v_pk_add_f32 v[76:77], v[76:77], v[82:83]
	v_pk_add_f32 v[78:79], v[78:79], v[84:85]
	s_waitcnt vmcnt(1)
	v_pk_add_f32 v[82:83], v[70:71], v[92:93]
	v_pk_add_f32 v[70:71], v[68:69], v[90:91]
	v_pk_mul_f32 v[68:69], v[76:77], v[76:77]
	v_pk_add_f32 v[72:73], v[72:73], v[86:87]
	s_waitcnt vmcnt(0)
	v_pk_add_f32 v[84:85], v[66:67], v[96:97]
	v_pk_add_f32 v[86:87], v[64:65], v[94:95]
	v_pk_mul_f32 v[64:65], v[78:79], v[78:79]
	v_add_f32_e32 v67, v68, v69
	v_add_f32_e32 v64, v64, v67
	v_pk_mul_f32 v[90:91], v[72:73], v[72:73]
	v_add_f32_e32 v64, v65, v64
	v_pk_add_f32 v[74:75], v[74:75], v[88:89]
	v_add_f32_e32 v64, v90, v64
	v_pk_mul_f32 v[88:89], v[74:75], v[74:75]
	v_add_f32_e32 v64, v91, v64
	v_add_f32_e32 v64, v88, v64
	v_pk_mul_f32 v[94:95], v[70:71], v[70:71]
	v_add_f32_e32 v64, v89, v64
	v_add_f32_e32 v64, v94, v64
	v_pk_mul_f32 v[92:93], v[82:83], v[82:83]
	v_add_f32_e32 v64, v95, v64
	v_add_f32_e32 v64, v92, v64
	v_pk_mul_f32 v[100:101], v[86:87], v[86:87]
	v_add_f32_e32 v64, v93, v64
	v_add_f32_e32 v64, v100, v64
	v_pk_mul_f32 v[96:97], v[84:85], v[84:85]
	v_add_f32_e32 v64, v101, v64
	v_add_f32_e32 v64, v96, v64
	v_add_f32_e32 v64, v97, v64
	ds_bpermute_b32 v65, v150, v64
	v_cvt_pk_bf16_f32 v66, v76, v77
	v_cvt_pk_bf16_f32 v67, v78, v79
	v_cvt_pk_bf16_f32 v68, v72, v73
	v_cvt_pk_bf16_f32 v69, v74, v75
	s_waitcnt lgkmcnt(0)
	v_add_f32_e32 v64, v64, v65
	ds_bpermute_b32 v65, v149, v64
	v_cvt_pk_bf16_f32 v70, v70, v71
	v_cvt_pk_bf16_f32 v71, v82, v83
	v_cvt_pk_bf16_f32 v72, v86, v87
	v_cvt_pk_bf16_f32 v73, v84, v85
	s_nop 1
	v_permlane16_swap_b32_e32 v66, v70
	v_permlane16_swap_b32_e32 v67, v71
	v_permlane16_swap_b32_e32 v68, v72
	v_permlane16_swap_b32_e32 v69, v73
	v_permlane32_swap_b32_e32 v66, v70
	v_permlane32_swap_b32_e32 v67, v71
	v_permlane32_swap_b32_e32 v68, v72
	v_permlane32_swap_b32_e32 v69, v73
	v_lshl_add_u64 v[238:239], v[98:99], 0, v[236:237]
	global_store_dwordx4 v[238:239], v[66:69], off
	global_store_dwordx4 v[238:239], v[70:73], off offset:64
	s_and_saveexec_b64 s[4:5], s[6:7]
	s_cbranch_execz .LBB0_1381
	v_lshlrev_b64 v[66:67], 6, v[80:81]
	v_lshl_add_u64 v[66:67], s[14:15], 0, v[66:67]
	v_lshl_add_u64 v[66:67], s[30:31], 2, v[66:67]
	s_lshl_b32 s8, s46, 2
	v_lshl_add_u64 v[66:67], v[66:67], 0, s[8:9]
	s_waitcnt lgkmcnt(0)
	v_add_f32_e32 v64, v64, v65
	global_store_dword v[66:67], v64, off
.LBB0_1381:
	s_or_b64 exec, exec, s[4:5]
	v_add_u32_e32 v64, 0x80, v140
	s_waitcnt lgkmcnt(0)
	v_ashrrev_i32_e32 v65, 31, v64
	v_readlane_b32 s60, v240, 5
	v_lshlrev_b64 v[66:67], 12, v[64:65]
	v_readlane_b32 s61, v240, 6
	v_lshlrev_b64 v[82:83], 11, v[64:65]
	v_lshl_add_u64 v[82:83], s[12:13], 0, v[82:83]
	v_lshl_add_u64 v[66:67], s[60:61], 0, v[66:67]
	v_lshl_add_u64 v[78:79], v[138:139], 2, v[66:67]
	global_load_dwordx4 v[66:69], v[78:79], off
	global_load_dwordx4 v[70:73], v[78:79], off offset:16
	global_load_dwordx4 v[74:77], v[78:79], off offset:32
	s_nop 0
	global_load_dwordx4 v[78:81], v[78:79], off offset:48
	v_lshl_add_u64 v[82:83], v[138:139], 1, v[82:83]
	v_readlane_b32 s62, v240, 7
	v_readlane_b32 s63, v240, 8
	s_waitcnt vmcnt(3)
	v_pk_add_f32 v[60:61], v[60:61], v[66:67]
	v_pk_add_f32 v[62:63], v[62:63], v[68:69]
	s_waitcnt vmcnt(1)
	v_pk_add_f32 v[66:67], v[54:55], v[76:77]
	v_pk_add_f32 v[54:55], v[52:53], v[74:75]
	v_pk_mul_f32 v[52:53], v[60:61], v[60:61]
	v_pk_add_f32 v[56:57], v[56:57], v[70:71]
	s_waitcnt vmcnt(0)
	v_pk_add_f32 v[68:69], v[50:51], v[80:81]
	v_pk_add_f32 v[70:71], v[48:49], v[78:79]
	v_pk_mul_f32 v[48:49], v[62:63], v[62:63]
	v_add_f32_e32 v51, v52, v53
	v_add_f32_e32 v48, v48, v51
	v_pk_mul_f32 v[74:75], v[56:57], v[56:57]
	v_add_f32_e32 v48, v49, v48
	v_pk_add_f32 v[58:59], v[58:59], v[72:73]
	v_add_f32_e32 v48, v74, v48
	v_pk_mul_f32 v[72:73], v[58:59], v[58:59]
	v_add_f32_e32 v48, v75, v48
	v_add_f32_e32 v48, v72, v48
	v_pk_mul_f32 v[78:79], v[54:55], v[54:55]
	v_add_f32_e32 v48, v73, v48
	v_add_f32_e32 v48, v78, v48
	v_pk_mul_f32 v[76:77], v[66:67], v[66:67]
	v_add_f32_e32 v48, v79, v48
	v_add_f32_e32 v48, v76, v48
	v_pk_mul_f32 v[84:85], v[70:71], v[70:71]
	v_add_f32_e32 v48, v77, v48
	v_add_f32_e32 v48, v84, v48
	v_pk_mul_f32 v[80:81], v[68:69], v[68:69]
	v_add_f32_e32 v48, v85, v48
	v_add_f32_e32 v48, v80, v48
	v_add_f32_e32 v48, v81, v48
	ds_bpermute_b32 v49, v150, v48
	v_cvt_pk_bf16_f32 v50, v60, v61
	v_cvt_pk_bf16_f32 v51, v62, v63
	v_cvt_pk_bf16_f32 v52, v56, v57
	v_cvt_pk_bf16_f32 v53, v58, v59
	s_waitcnt lgkmcnt(0)
	v_add_f32_e32 v48, v48, v49
	ds_bpermute_b32 v49, v149, v48
	v_cvt_pk_bf16_f32 v54, v54, v55
	v_cvt_pk_bf16_f32 v55, v66, v67
	v_cvt_pk_bf16_f32 v56, v70, v71
	v_cvt_pk_bf16_f32 v57, v68, v69
	s_nop 1
	v_permlane16_swap_b32_e32 v50, v54
	v_permlane16_swap_b32_e32 v51, v55
	v_permlane16_swap_b32_e32 v52, v56
	v_permlane16_swap_b32_e32 v53, v57
	v_permlane32_swap_b32_e32 v50, v54
	v_permlane32_swap_b32_e32 v51, v55
	v_permlane32_swap_b32_e32 v52, v56
	v_permlane32_swap_b32_e32 v53, v57
	v_lshl_add_u64 v[238:239], v[82:83], 0, v[236:237]
	global_store_dwordx4 v[238:239], v[50:53], off
	global_store_dwordx4 v[238:239], v[54:57], off offset:64
	s_and_saveexec_b64 s[4:5], s[6:7]
	s_cbranch_execz .LBB0_1383
	v_lshlrev_b64 v[50:51], 6, v[64:65]
	v_lshl_add_u64 v[50:51], s[14:15], 0, v[50:51]
	v_lshl_add_u64 v[50:51], s[30:31], 2, v[50:51]
	s_lshl_b32 s8, s46, 2
	v_lshl_add_u64 v[50:51], v[50:51], 0, s[8:9]
	s_waitcnt lgkmcnt(0)
	v_add_f32_e32 v48, v48, v49
	global_store_dword v[50:51], v48, off
.LBB0_1383:
	s_or_b64 exec, exec, s[4:5]
	v_add_u32_e32 v48, 0x90, v140
	s_waitcnt lgkmcnt(0)
	v_ashrrev_i32_e32 v49, 31, v48
	v_readlane_b32 s60, v240, 5
	v_lshlrev_b64 v[50:51], 12, v[48:49]
	v_readlane_b32 s61, v240, 6
	v_lshlrev_b64 v[66:67], 11, v[48:49]
	v_lshl_add_u64 v[66:67], s[12:13], 0, v[66:67]
	v_lshl_add_u64 v[50:51], s[60:61], 0, v[50:51]
	v_lshl_add_u64 v[62:63], v[138:139], 2, v[50:51]
	global_load_dwordx4 v[50:53], v[62:63], off
	global_load_dwordx4 v[54:57], v[62:63], off offset:16
	global_load_dwordx4 v[58:61], v[62:63], off offset:32
	s_nop 0
	global_load_dwordx4 v[62:65], v[62:63], off offset:48
	v_lshl_add_u64 v[66:67], v[138:139], 1, v[66:67]
	v_readlane_b32 s62, v240, 7
	v_readlane_b32 s63, v240, 8
	s_waitcnt vmcnt(3)
	v_pk_add_f32 v[44:45], v[44:45], v[50:51]
	v_pk_add_f32 v[46:47], v[46:47], v[52:53]
	s_waitcnt vmcnt(1)
	v_pk_add_f32 v[50:51], v[38:39], v[60:61]
	v_pk_add_f32 v[38:39], v[36:37], v[58:59]
	v_pk_mul_f32 v[36:37], v[44:45], v[44:45]
	v_pk_add_f32 v[40:41], v[40:41], v[54:55]
	s_waitcnt vmcnt(0)
	v_pk_add_f32 v[52:53], v[34:35], v[64:65]
	v_pk_add_f32 v[54:55], v[32:33], v[62:63]
	v_pk_mul_f32 v[32:33], v[46:47], v[46:47]
	v_add_f32_e32 v35, v36, v37
	v_add_f32_e32 v32, v32, v35
	v_pk_mul_f32 v[58:59], v[40:41], v[40:41]
	v_add_f32_e32 v32, v33, v32
	v_pk_add_f32 v[42:43], v[42:43], v[56:57]
	v_add_f32_e32 v32, v58, v32
	v_pk_mul_f32 v[56:57], v[42:43], v[42:43]
	v_add_f32_e32 v32, v59, v32
	v_add_f32_e32 v32, v56, v32
	v_pk_mul_f32 v[62:63], v[38:39], v[38:39]
	v_add_f32_e32 v32, v57, v32
	v_add_f32_e32 v32, v62, v32
	v_pk_mul_f32 v[60:61], v[50:51], v[50:51]
	v_add_f32_e32 v32, v63, v32
	v_add_f32_e32 v32, v60, v32
	v_pk_mul_f32 v[68:69], v[54:55], v[54:55]
	v_add_f32_e32 v32, v61, v32
	v_add_f32_e32 v32, v68, v32
	v_pk_mul_f32 v[64:65], v[52:53], v[52:53]
	v_add_f32_e32 v32, v69, v32
	v_add_f32_e32 v32, v64, v32
	v_add_f32_e32 v32, v65, v32
	ds_bpermute_b32 v33, v150, v32
	v_cvt_pk_bf16_f32 v34, v44, v45
	v_cvt_pk_bf16_f32 v35, v46, v47
	v_cvt_pk_bf16_f32 v36, v40, v41
	v_cvt_pk_bf16_f32 v37, v42, v43
	s_waitcnt lgkmcnt(0)
	v_add_f32_e32 v32, v32, v33
	ds_bpermute_b32 v33, v149, v32
	v_cvt_pk_bf16_f32 v38, v38, v39
	v_cvt_pk_bf16_f32 v39, v50, v51
	v_cvt_pk_bf16_f32 v40, v54, v55
	v_cvt_pk_bf16_f32 v41, v52, v53
	s_nop 1
	v_permlane16_swap_b32_e32 v34, v38
	v_permlane16_swap_b32_e32 v35, v39
	v_permlane16_swap_b32_e32 v36, v40
	v_permlane16_swap_b32_e32 v37, v41
	v_permlane32_swap_b32_e32 v34, v38
	v_permlane32_swap_b32_e32 v35, v39
	v_permlane32_swap_b32_e32 v36, v40
	v_permlane32_swap_b32_e32 v37, v41
	v_lshl_add_u64 v[238:239], v[66:67], 0, v[236:237]
	global_store_dwordx4 v[238:239], v[34:37], off
	global_store_dwordx4 v[238:239], v[38:41], off offset:64
	s_and_saveexec_b64 s[4:5], s[6:7]
	s_cbranch_execz .LBB0_1385
	v_lshlrev_b64 v[34:35], 6, v[48:49]
	v_lshl_add_u64 v[34:35], s[14:15], 0, v[34:35]
	v_lshl_add_u64 v[34:35], s[30:31], 2, v[34:35]
	s_lshl_b32 s8, s46, 2
	v_lshl_add_u64 v[34:35], v[34:35], 0, s[8:9]
	s_waitcnt lgkmcnt(0)
	v_add_f32_e32 v32, v32, v33
	global_store_dword v[34:35], v32, off
.LBB0_1385:
	s_or_b64 exec, exec, s[4:5]
	v_add_u32_e32 v32, 0xa0, v140
	s_waitcnt lgkmcnt(0)
	v_ashrrev_i32_e32 v33, 31, v32
	v_readlane_b32 s60, v240, 5
	v_lshlrev_b64 v[34:35], 12, v[32:33]
	v_readlane_b32 s61, v240, 6
	v_lshlrev_b64 v[50:51], 11, v[32:33]
	v_lshl_add_u64 v[50:51], s[12:13], 0, v[50:51]
	v_lshl_add_u64 v[34:35], s[60:61], 0, v[34:35]
	v_lshl_add_u64 v[46:47], v[138:139], 2, v[34:35]
	global_load_dwordx4 v[34:37], v[46:47], off
	global_load_dwordx4 v[38:41], v[46:47], off offset:16
	global_load_dwordx4 v[42:45], v[46:47], off offset:32
	s_nop 0
	global_load_dwordx4 v[46:49], v[46:47], off offset:48
	v_lshl_add_u64 v[50:51], v[138:139], 1, v[50:51]
	v_readlane_b32 s62, v240, 7
	v_readlane_b32 s63, v240, 8
	s_waitcnt vmcnt(3)
	v_pk_add_f32 v[28:29], v[28:29], v[34:35]
	v_pk_add_f32 v[30:31], v[30:31], v[36:37]
	s_waitcnt vmcnt(1)
	v_pk_add_f32 v[34:35], v[22:23], v[44:45]
	v_pk_add_f32 v[22:23], v[20:21], v[42:43]
	v_pk_mul_f32 v[20:21], v[28:29], v[28:29]
	v_pk_add_f32 v[24:25], v[24:25], v[38:39]
	s_waitcnt vmcnt(0)
	v_pk_add_f32 v[36:37], v[18:19], v[48:49]
	v_pk_add_f32 v[38:39], v[16:17], v[46:47]
	v_pk_mul_f32 v[16:17], v[30:31], v[30:31]
	v_add_f32_e32 v19, v20, v21
	v_add_f32_e32 v16, v16, v19
	v_pk_mul_f32 v[42:43], v[24:25], v[24:25]
	v_add_f32_e32 v16, v17, v16
	v_pk_add_f32 v[26:27], v[26:27], v[40:41]
	v_add_f32_e32 v16, v42, v16
	v_pk_mul_f32 v[40:41], v[26:27], v[26:27]
	v_add_f32_e32 v16, v43, v16
	v_add_f32_e32 v16, v40, v16
	v_pk_mul_f32 v[46:47], v[22:23], v[22:23]
	v_add_f32_e32 v16, v41, v16
	v_add_f32_e32 v16, v46, v16
	v_pk_mul_f32 v[44:45], v[34:35], v[34:35]
	v_add_f32_e32 v16, v47, v16
	v_add_f32_e32 v16, v44, v16
	v_pk_mul_f32 v[52:53], v[38:39], v[38:39]
	v_add_f32_e32 v16, v45, v16
	v_add_f32_e32 v16, v52, v16
	v_pk_mul_f32 v[48:49], v[36:37], v[36:37]
	v_add_f32_e32 v16, v53, v16
	v_add_f32_e32 v16, v48, v16
	v_add_f32_e32 v16, v49, v16
	ds_bpermute_b32 v17, v150, v16
	v_cvt_pk_bf16_f32 v18, v28, v29
	v_cvt_pk_bf16_f32 v19, v30, v31
	v_cvt_pk_bf16_f32 v20, v24, v25
	v_cvt_pk_bf16_f32 v21, v26, v27
	s_waitcnt lgkmcnt(0)
	v_add_f32_e32 v16, v16, v17
	ds_bpermute_b32 v17, v149, v16
	v_cvt_pk_bf16_f32 v22, v22, v23
	v_cvt_pk_bf16_f32 v23, v34, v35
	v_cvt_pk_bf16_f32 v24, v38, v39
	v_cvt_pk_bf16_f32 v25, v36, v37
	s_nop 1
	v_permlane16_swap_b32_e32 v18, v22
	v_permlane16_swap_b32_e32 v19, v23
	v_permlane16_swap_b32_e32 v20, v24
	v_permlane16_swap_b32_e32 v21, v25
	v_permlane32_swap_b32_e32 v18, v22
	v_permlane32_swap_b32_e32 v19, v23
	v_permlane32_swap_b32_e32 v20, v24
	v_permlane32_swap_b32_e32 v21, v25
	v_lshl_add_u64 v[238:239], v[50:51], 0, v[236:237]
	global_store_dwordx4 v[238:239], v[18:21], off
	global_store_dwordx4 v[238:239], v[22:25], off offset:64
	s_and_saveexec_b64 s[4:5], s[6:7]
	s_cbranch_execz .LBB0_1387
	v_lshlrev_b64 v[18:19], 6, v[32:33]
	v_lshl_add_u64 v[18:19], s[14:15], 0, v[18:19]
	v_lshl_add_u64 v[18:19], s[30:31], 2, v[18:19]
	s_lshl_b32 s8, s46, 2
	v_lshl_add_u64 v[18:19], v[18:19], 0, s[8:9]
	s_waitcnt lgkmcnt(0)
	v_add_f32_e32 v16, v16, v17
	global_store_dword v[18:19], v16, off
.LBB0_1387:
	s_or_b64 exec, exec, s[4:5]
	v_add_u32_e32 v16, 0xb0, v140
	s_waitcnt lgkmcnt(0)
	v_ashrrev_i32_e32 v17, 31, v16
	v_readlane_b32 s60, v240, 5
	v_lshlrev_b64 v[18:19], 12, v[16:17]
	v_readlane_b32 s61, v240, 6
	v_lshlrev_b64 v[34:35], 11, v[16:17]
	v_lshl_add_u64 v[34:35], s[12:13], 0, v[34:35]
	v_lshl_add_u64 v[18:19], s[60:61], 0, v[18:19]
	v_lshl_add_u64 v[30:31], v[138:139], 2, v[18:19]
	global_load_dwordx4 v[18:21], v[30:31], off
	global_load_dwordx4 v[22:25], v[30:31], off offset:16
	global_load_dwordx4 v[26:29], v[30:31], off offset:32
	s_nop 0
	global_load_dwordx4 v[30:33], v[30:31], off offset:48
	v_lshl_add_u64 v[34:35], v[138:139], 1, v[34:35]
	v_readlane_b32 s62, v240, 7
	v_readlane_b32 s63, v240, 8
	s_waitcnt vmcnt(3)
	v_pk_add_f32 v[12:13], v[12:13], v[18:19]
	v_pk_add_f32 v[14:15], v[14:15], v[20:21]
	s_waitcnt vmcnt(1)
	v_pk_add_f32 v[18:19], v[6:7], v[28:29]
	v_pk_add_f32 v[6:7], v[4:5], v[26:27]
	v_pk_mul_f32 v[4:5], v[12:13], v[12:13]
	v_pk_add_f32 v[8:9], v[8:9], v[22:23]
	s_waitcnt vmcnt(0)
	v_pk_add_f32 v[20:21], v[2:3], v[32:33]
	v_pk_add_f32 v[22:23], v[0:1], v[30:31]
	v_pk_mul_f32 v[0:1], v[14:15], v[14:15]
	v_add_f32_e32 v3, v4, v5
	v_add_f32_e32 v0, v0, v3
	v_pk_mul_f32 v[26:27], v[8:9], v[8:9]
	v_add_f32_e32 v0, v1, v0
	v_pk_add_f32 v[10:11], v[10:11], v[24:25]
	v_add_f32_e32 v0, v26, v0
	v_pk_mul_f32 v[24:25], v[10:11], v[10:11]
	v_add_f32_e32 v0, v27, v0
	v_add_f32_e32 v0, v24, v0
	v_pk_mul_f32 v[30:31], v[6:7], v[6:7]
	v_add_f32_e32 v0, v25, v0
	v_add_f32_e32 v0, v30, v0
	v_pk_mul_f32 v[28:29], v[18:19], v[18:19]
	v_add_f32_e32 v0, v31, v0
	v_add_f32_e32 v0, v28, v0
	v_pk_mul_f32 v[36:37], v[22:23], v[22:23]
	v_add_f32_e32 v0, v29, v0
	v_add_f32_e32 v0, v36, v0
	v_pk_mul_f32 v[32:33], v[20:21], v[20:21]
	v_add_f32_e32 v0, v37, v0
	v_add_f32_e32 v0, v32, v0
	v_add_f32_e32 v0, v33, v0
	ds_bpermute_b32 v1, v150, v0
	v_cvt_pk_bf16_f32 v2, v12, v13
	v_cvt_pk_bf16_f32 v3, v14, v15
	v_cvt_pk_bf16_f32 v4, v8, v9
	v_cvt_pk_bf16_f32 v5, v10, v11
	s_waitcnt lgkmcnt(0)
	v_add_f32_e32 v0, v0, v1
	ds_bpermute_b32 v1, v149, v0
	v_cvt_pk_bf16_f32 v6, v6, v7
	v_cvt_pk_bf16_f32 v7, v18, v19
	v_cvt_pk_bf16_f32 v8, v22, v23
	v_cvt_pk_bf16_f32 v9, v20, v21
	s_nop 1
	v_permlane16_swap_b32_e32 v2, v6
	v_permlane16_swap_b32_e32 v3, v7
	v_permlane16_swap_b32_e32 v4, v8
	v_permlane16_swap_b32_e32 v5, v9
	v_permlane32_swap_b32_e32 v2, v6
	v_permlane32_swap_b32_e32 v3, v7
	v_permlane32_swap_b32_e32 v4, v8
	v_permlane32_swap_b32_e32 v5, v9
	v_lshl_add_u64 v[238:239], v[34:35], 0, v[236:237]
	global_store_dwordx4 v[238:239], v[2:5], off
	global_store_dwordx4 v[238:239], v[6:9], off offset:64
	s_and_saveexec_b64 s[4:5], s[6:7]
	s_cbranch_execz .LBB0_1389
	v_lshlrev_b64 v[2:3], 6, v[16:17]
	v_lshl_add_u64 v[2:3], s[14:15], 0, v[2:3]
	v_lshl_add_u64 v[2:3], s[30:31], 2, v[2:3]
	s_lshl_b32 s8, s46, 2
	v_lshl_add_u64 v[2:3], v[2:3], 0, s[8:9]
	s_waitcnt lgkmcnt(0)
	v_add_f32_e32 v0, v0, v1
	global_store_dword v[2:3], v0, off

.LBB0_1555:
	v_and_b32_e32 v236, 48, v144
	v_sub_u32_e32 v236, 0, v236
	v_ashrrev_i32_e32 v237, 31, v236
	v_lshl_add_u32 v140, s55, 8, v142
	v_ashrrev_i32_e32 v141, 31, v140
	v_lshl_or_b32 v138, s8, 8, v144
	v_lshlrev_b64 v[150:151], 11, v[140:141]
	v_ashrrev_i32_e32 v139, 31, v138
	v_lshl_add_u64 v[150:151], s[12:13], 0, v[150:151]
	v_lshl_add_u64 v[160:161], v[138:139], 1, v[150:151]
	global_load_dwordx4 v[152:155], v[160:161], off
	global_load_dwordx4 v[156:159], v[160:161], off offset:16
	v_and_b32_e32 v150, 64, v148
	v_xor_b32_e32 v149, 16, v148
	v_add_u32_e32 v150, 64, v150
	v_cmp_lt_i32_e32 vcc, v149, v150
	v_xor_b32_e32 v151, 32, v148
	s_lshl_b32 s26, s8, 2
	v_cndmask_b32_e32 v149, v148, v149, vcc
	v_cmp_lt_i32_e32 vcc, v151, v150
	v_lshlrev_b32_e32 v150, 2, v149
	s_ashr_i32 s27, s26, 31
	v_cndmask_b32_e32 v151, v148, v151, vcc
	v_lshlrev_b32_e32 v149, 2, v151
	s_waitcnt vmcnt(0)
	v_lshlrev_b32_e32 v162, 16, v152
	v_and_b32_e32 v163, 0xffff0000, v152
	v_lshlrev_b32_e32 v152, 16, v153
	v_and_b32_e32 v153, 0xffff0000, v153
	v_lshlrev_b32_e32 v164, 16, v154
	v_and_b32_e32 v165, 0xffff0000, v154
	v_lshlrev_b32_e32 v154, 16, v155
	v_and_b32_e32 v155, 0xffff0000, v155
	v_lshlrev_b32_e32 v166, 16, v156
	v_and_b32_e32 v167, 0xffff0000, v156
	v_lshlrev_b32_e32 v156, 16, v157
	v_and_b32_e32 v157, 0xffff0000, v157
	v_lshlrev_b32_e32 v168, 16, v158
	v_and_b32_e32 v169, 0xffff0000, v158
	v_pk_add_f32 v[120:121], v[120:121], v[162:163]
	v_pk_add_f32 v[122:123], v[122:123], v[152:153]
	v_pk_add_f32 v[126:127], v[126:127], v[154:155]
	v_pk_add_f32 v[154:155], v[118:119], v[156:157]
	v_pk_add_f32 v[156:157], v[112:113], v[168:169]
	v_pk_mul_f32 v[112:113], v[120:121], v[120:121]
	v_pk_add_f32 v[152:153], v[116:117], v[166:167]
	v_pk_mul_f32 v[116:117], v[122:123], v[122:123]
	v_add_f32_e32 v112, v112, v113
	v_pk_add_f32 v[124:125], v[124:125], v[164:165]
	v_add_f32_e32 v112, v116, v112
	v_pk_mul_f32 v[118:119], v[124:125], v[124:125]
	v_add_f32_e32 v112, v117, v112
	v_add_f32_e32 v112, v118, v112
	v_pk_mul_f32 v[162:163], v[126:127], v[126:127]
	v_add_f32_e32 v112, v119, v112
	v_add_f32_e32 v112, v162, v112
	v_pk_mul_f32 v[164:165], v[152:153], v[152:153]
	v_add_f32_e32 v112, v163, v112
	v_add_f32_e32 v112, v164, v112
	v_pk_mul_f32 v[166:167], v[154:155], v[154:155]
	v_add_f32_e32 v112, v165, v112
	v_add_f32_e32 v112, v166, v112
	v_lshlrev_b32_e32 v158, 16, v159
	v_and_b32_e32 v159, 0xffff0000, v159
	v_pk_mul_f32 v[168:169], v[156:157], v[156:157]
	v_add_f32_e32 v112, v167, v112
	v_pk_add_f32 v[158:159], v[114:115], v[158:159]
	v_add_f32_e32 v112, v168, v112
	v_pk_mul_f32 v[170:171], v[158:159], v[158:159]
	v_add_f32_e32 v112, v169, v112
	v_add_f32_e32 v112, v170, v112
	v_add_f32_e32 v112, v171, v112
	ds_bpermute_b32 v113, v150, v112
	v_cvt_pk_bf16_f32 v114, v120, v121
	v_cvt_pk_bf16_f32 v115, v122, v123
	v_cvt_pk_bf16_f32 v116, v124, v125
	v_cvt_pk_bf16_f32 v117, v126, v127
	s_waitcnt lgkmcnt(0)
	v_add_f32_e32 v112, v112, v113
	ds_bpermute_b32 v113, v149, v112
	v_cvt_pk_bf16_f32 v118, v152, v153
	v_cvt_pk_bf16_f32 v119, v154, v155
	v_cvt_pk_bf16_f32 v120, v156, v157
	v_cvt_pk_bf16_f32 v121, v158, v159
	s_nop 1
	v_permlane16_swap_b32_e32 v114, v118
	v_permlane16_swap_b32_e32 v115, v119
	v_permlane16_swap_b32_e32 v116, v120
	v_permlane16_swap_b32_e32 v117, v121
	v_permlane32_swap_b32_e32 v114, v118
	v_permlane32_swap_b32_e32 v115, v119
	v_permlane32_swap_b32_e32 v116, v120
	v_permlane32_swap_b32_e32 v117, v121
	v_lshl_add_u64 v[238:239], v[160:161], 0, v[236:237]
	global_store_dwordx4 v[238:239], v[114:117], off
	global_store_dwordx4 v[238:239], v[118:121], off offset:64
	s_and_saveexec_b64 s[4:5], s[6:7]
	s_cbranch_execz .LBB0_1557
	s_waitcnt lgkmcnt(0)
	v_add_f32_e32 v114, v112, v113
	v_lshlrev_b64 v[112:113], 6, v[140:141]
	v_lshl_add_u64 v[112:113], s[14:15], 0, v[112:113]
	v_lshl_add_u64 v[112:113], s[26:27], 2, v[112:113]
	s_lshl_b32 s8, s40, 2
	v_lshl_add_u64 v[112:113], v[112:113], 0, s[8:9]
	global_store_dword v[112:113], v114, off
.LBB0_1557:
	s_or_b64 exec, exec, s[4:5]
	v_or_b32_e32 v112, 16, v140
	s_waitcnt lgkmcnt(0)
	v_ashrrev_i32_e32 v113, 31, v112
	v_lshlrev_b64 v[114:115], 11, v[112:113]
	v_lshl_add_u64 v[114:115], s[12:13], 0, v[114:115]
	v_lshl_add_u64 v[122:123], v[138:139], 1, v[114:115]
	global_load_dwordx4 v[114:117], v[122:123], off
	global_load_dwordx4 v[118:121], v[122:123], off offset:16
	s_waitcnt vmcnt(1)
	v_lshlrev_b32_e32 v124, 16, v114
	v_and_b32_e32 v125, 0xffff0000, v114
	v_lshlrev_b32_e32 v114, 16, v115
	v_and_b32_e32 v115, 0xffff0000, v115
	v_lshlrev_b32_e32 v126, 16, v116
	v_and_b32_e32 v127, 0xffff0000, v116
	v_lshlrev_b32_e32 v116, 16, v117
	v_and_b32_e32 v117, 0xffff0000, v117
	s_waitcnt vmcnt(0)
	v_lshlrev_b32_e32 v152, 16, v118
	v_and_b32_e32 v153, 0xffff0000, v118
	v_lshlrev_b32_e32 v118, 16, v119
	v_and_b32_e32 v119, 0xffff0000, v119
	v_lshlrev_b32_e32 v154, 16, v120
	v_and_b32_e32 v155, 0xffff0000, v120
	v_pk_add_f32 v[108:109], v[108:109], v[124:125]
	v_pk_add_f32 v[110:111], v[110:111], v[114:115]
	v_pk_add_f32 v[106:107], v[106:107], v[116:117]
	v_pk_add_f32 v[116:117], v[102:103], v[118:119]
	v_pk_add_f32 v[118:119], v[96:97], v[154:155]
	v_pk_mul_f32 v[96:97], v[108:109], v[108:109]
	v_pk_add_f32 v[114:115], v[100:101], v[152:153]
	v_pk_mul_f32 v[100:101], v[110:111], v[110:111]
	v_add_f32_e32 v96, v96, v97
	v_pk_add_f32 v[104:105], v[104:105], v[126:127]
	v_add_f32_e32 v96, v100, v96
	v_pk_mul_f32 v[102:103], v[104:105], v[104:105]
	v_add_f32_e32 v96, v101, v96
	v_add_f32_e32 v96, v102, v96
	v_pk_mul_f32 v[124:125], v[106:107], v[106:107]
	v_add_f32_e32 v96, v103, v96
	v_add_f32_e32 v96, v124, v96
	v_pk_mul_f32 v[126:127], v[114:115], v[114:115]
	v_add_f32_e32 v96, v125, v96
	v_add_f32_e32 v96, v126, v96
	v_pk_mul_f32 v[152:153], v[116:117], v[116:117]
	v_add_f32_e32 v96, v127, v96
	v_add_f32_e32 v96, v152, v96
	v_lshlrev_b32_e32 v120, 16, v121
	v_and_b32_e32 v121, 0xffff0000, v121
	v_pk_mul_f32 v[154:155], v[118:119], v[118:119]
	v_add_f32_e32 v96, v153, v96
	v_pk_add_f32 v[120:121], v[98:99], v[120:121]
	v_add_f32_e32 v96, v154, v96
	v_pk_mul_f32 v[156:157], v[120:121], v[120:121]
	v_add_f32_e32 v96, v155, v96
	v_add_f32_e32 v96, v156, v96
	v_add_f32_e32 v96, v157, v96
	ds_bpermute_b32 v97, v150, v96
	v_cvt_pk_bf16_f32 v98, v108, v109
	v_cvt_pk_bf16_f32 v99, v110, v111
	v_cvt_pk_bf16_f32 v100, v104, v105
	v_cvt_pk_bf16_f32 v101, v106, v107
	s_waitcnt lgkmcnt(0)
	v_add_f32_e32 v96, v96, v97
	ds_bpermute_b32 v97, v149, v96
	v_cvt_pk_bf16_f32 v102, v114, v115
	v_cvt_pk_bf16_f32 v103, v116, v117
	v_cvt_pk_bf16_f32 v104, v118, v119
	v_cvt_pk_bf16_f32 v105, v120, v121
	s_nop 1
	v_permlane16_swap_b32_e32 v98, v102
	v_permlane16_swap_b32_e32 v99, v103
	v_permlane16_swap_b32_e32 v100, v104
	v_permlane16_swap_b32_e32 v101, v105
	v_permlane32_swap_b32_e32 v98, v102
	v_permlane32_swap_b32_e32 v99, v103
	v_permlane32_swap_b32_e32 v100, v104
	v_permlane32_swap_b32_e32 v101, v105
	v_lshl_add_u64 v[238:239], v[122:123], 0, v[236:237]
	global_store_dwordx4 v[238:239], v[98:101], off
	global_store_dwordx4 v[238:239], v[102:105], off offset:64
	s_and_saveexec_b64 s[4:5], s[6:7]
	s_cbranch_execz .LBB0_1559
	s_waitcnt lgkmcnt(0)
	v_add_f32_e32 v98, v96, v97
	v_lshlrev_b64 v[96:97], 6, v[112:113]
	v_lshl_add_u64 v[96:97], s[14:15], 0, v[96:97]
	v_lshl_add_u64 v[96:97], s[26:27], 2, v[96:97]
	s_lshl_b32 s8, s40, 2
	v_lshl_add_u64 v[96:97], v[96:97], 0, s[8:9]
	global_store_dword v[96:97], v98, off
.LBB0_1559:
	s_or_b64 exec, exec, s[4:5]
	v_or_b32_e32 v96, 32, v140
	s_waitcnt lgkmcnt(0)
	v_ashrrev_i32_e32 v97, 31, v96
	v_lshlrev_b64 v[98:99], 11, v[96:97]
	v_lshl_add_u64 v[98:99], s[12:13], 0, v[98:99]
	v_lshl_add_u64 v[106:107], v[138:139], 1, v[98:99]
	global_load_dwordx4 v[98:101], v[106:107], off
	global_load_dwordx4 v[102:105], v[106:107], off offset:16
	s_waitcnt vmcnt(1)
	v_lshlrev_b32_e32 v108, 16, v98
	v_and_b32_e32 v109, 0xffff0000, v98
	v_lshlrev_b32_e32 v98, 16, v99
	v_and_b32_e32 v99, 0xffff0000, v99
	v_lshlrev_b32_e32 v110, 16, v100
	v_and_b32_e32 v111, 0xffff0000, v100
	v_lshlrev_b32_e32 v100, 16, v101
	v_and_b32_e32 v101, 0xffff0000, v101
	s_waitcnt vmcnt(0)
	v_lshlrev_b32_e32 v112, 16, v102
	v_and_b32_e32 v113, 0xffff0000, v102
	v_lshlrev_b32_e32 v102, 16, v103
	v_and_b32_e32 v103, 0xffff0000, v103
	v_lshlrev_b32_e32 v114, 16, v104
	v_and_b32_e32 v115, 0xffff0000, v104
	v_pk_add_f32 v[92:93], v[92:93], v[108:109]
	v_pk_add_f32 v[94:95], v[94:95], v[98:99]
	v_pk_add_f32 v[90:91], v[90:91], v[100:101]
	v_pk_add_f32 v[100:101], v[86:87], v[102:103]
	v_pk_add_f32 v[102:103], v[80:81], v[114:115]
	v_pk_mul_f32 v[80:81], v[92:93], v[92:93]
	v_pk_add_f32 v[98:99], v[84:85], v[112:113]
	v_pk_mul_f32 v[84:85], v[94:95], v[94:95]
	v_add_f32_e32 v80, v80, v81
	v_pk_add_f32 v[88:89], v[88:89], v[110:111]
	v_add_f32_e32 v80, v84, v80
	v_pk_mul_f32 v[86:87], v[88:89], v[88:89]
	v_add_f32_e32 v80, v85, v80
	v_add_f32_e32 v80, v86, v80
	v_pk_mul_f32 v[108:109], v[90:91], v[90:91]
	v_add_f32_e32 v80, v87, v80
	v_add_f32_e32 v80, v108, v80
	v_pk_mul_f32 v[110:111], v[98:99], v[98:99]
	v_add_f32_e32 v80, v109, v80
	v_add_f32_e32 v80, v110, v80
	v_pk_mul_f32 v[112:113], v[100:101], v[100:101]
	v_add_f32_e32 v80, v111, v80
	v_add_f32_e32 v80, v112, v80
	v_lshlrev_b32_e32 v104, 16, v105
	v_and_b32_e32 v105, 0xffff0000, v105
	v_pk_mul_f32 v[114:115], v[102:103], v[102:103]
	v_add_f32_e32 v80, v113, v80
	v_pk_add_f32 v[104:105], v[82:83], v[104:105]
	v_add_f32_e32 v80, v114, v80
	v_pk_mul_f32 v[116:117], v[104:105], v[104:105]
	v_add_f32_e32 v80, v115, v80
	v_add_f32_e32 v80, v116, v80
	v_add_f32_e32 v80, v117, v80
	ds_bpermute_b32 v81, v150, v80
	v_cvt_pk_bf16_f32 v82, v92, v93
	v_cvt_pk_bf16_f32 v83, v94, v95
	v_cvt_pk_bf16_f32 v84, v88, v89
	v_cvt_pk_bf16_f32 v85, v90, v91
	s_waitcnt lgkmcnt(0)
	v_add_f32_e32 v80, v80, v81
	ds_bpermute_b32 v81, v149, v80
	v_cvt_pk_bf16_f32 v86, v98, v99
	v_cvt_pk_bf16_f32 v87, v100, v101
	v_cvt_pk_bf16_f32 v88, v102, v103
	v_cvt_pk_bf16_f32 v89, v104, v105
	s_nop 1
	v_permlane16_swap_b32_e32 v82, v86
	v_permlane16_swap_b32_e32 v83, v87
	v_permlane16_swap_b32_e32 v84, v88
	v_permlane16_swap_b32_e32 v85, v89
	v_permlane32_swap_b32_e32 v82, v86
	v_permlane32_swap_b32_e32 v83, v87
	v_permlane32_swap_b32_e32 v84, v88
	v_permlane32_swap_b32_e32 v85, v89
	v_lshl_add_u64 v[238:239], v[106:107], 0, v[236:237]
	global_store_dwordx4 v[238:239], v[82:85], off
	global_store_dwordx4 v[238:239], v[86:89], off offset:64
	s_and_saveexec_b64 s[4:5], s[6:7]
	s_cbranch_execz .LBB0_1561
	s_waitcnt lgkmcnt(0)
	v_add_f32_e32 v82, v80, v81
	v_lshlrev_b64 v[80:81], 6, v[96:97]
	v_lshl_add_u64 v[80:81], s[14:15], 0, v[80:81]
	v_lshl_add_u64 v[80:81], s[26:27], 2, v[80:81]
	s_lshl_b32 s8, s40, 2
	v_lshl_add_u64 v[80:81], v[80:81], 0, s[8:9]
	global_store_dword v[80:81], v82, off
.LBB0_1561:
	s_or_b64 exec, exec, s[4:5]
	v_or_b32_e32 v80, 48, v140
	s_waitcnt lgkmcnt(0)
	v_ashrrev_i32_e32 v81, 31, v80
	v_lshlrev_b64 v[82:83], 11, v[80:81]
	v_lshl_add_u64 v[82:83], s[12:13], 0, v[82:83]
	v_lshl_add_u64 v[90:91], v[138:139], 1, v[82:83]
	global_load_dwordx4 v[82:85], v[90:91], off
	global_load_dwordx4 v[86:89], v[90:91], off offset:16
	s_waitcnt vmcnt(1)
	v_lshlrev_b32_e32 v92, 16, v82
	v_and_b32_e32 v93, 0xffff0000, v82
	v_lshlrev_b32_e32 v82, 16, v83
	v_and_b32_e32 v83, 0xffff0000, v83
	v_lshlrev_b32_e32 v94, 16, v84
	v_and_b32_e32 v95, 0xffff0000, v84
	v_lshlrev_b32_e32 v84, 16, v85
	v_and_b32_e32 v85, 0xffff0000, v85
	s_waitcnt vmcnt(0)
	v_lshlrev_b32_e32 v96, 16, v86
	v_and_b32_e32 v97, 0xffff0000, v86
	v_lshlrev_b32_e32 v86, 16, v87
	v_and_b32_e32 v87, 0xffff0000, v87
	v_lshlrev_b32_e32 v98, 16, v88
	v_and_b32_e32 v99, 0xffff0000, v88
	v_pk_add_f32 v[76:77], v[76:77], v[92:93]
	v_pk_add_f32 v[78:79], v[78:79], v[82:83]
	v_pk_add_f32 v[74:75], v[74:75], v[84:85]
	v_pk_add_f32 v[84:85], v[70:71], v[86:87]
	v_pk_add_f32 v[86:87], v[64:65], v[98:99]
	v_pk_mul_f32 v[64:65], v[76:77], v[76:77]
	v_pk_add_f32 v[82:83], v[68:69], v[96:97]
	v_pk_mul_f32 v[68:69], v[78:79], v[78:79]
	v_add_f32_e32 v64, v64, v65
	v_pk_add_f32 v[72:73], v[72:73], v[94:95]
	v_add_f32_e32 v64, v68, v64
	v_pk_mul_f32 v[70:71], v[72:73], v[72:73]
	v_add_f32_e32 v64, v69, v64
	v_add_f32_e32 v64, v70, v64
	v_pk_mul_f32 v[92:93], v[74:75], v[74:75]
	v_add_f32_e32 v64, v71, v64
	v_add_f32_e32 v64, v92, v64
	v_pk_mul_f32 v[94:95], v[82:83], v[82:83]
	v_add_f32_e32 v64, v93, v64
	v_add_f32_e32 v64, v94, v64
	v_pk_mul_f32 v[96:97], v[84:85], v[84:85]
	v_add_f32_e32 v64, v95, v64
	v_add_f32_e32 v64, v96, v64
	v_lshlrev_b32_e32 v88, 16, v89
	v_and_b32_e32 v89, 0xffff0000, v89
	v_pk_mul_f32 v[98:99], v[86:87], v[86:87]
	v_add_f32_e32 v64, v97, v64
	v_pk_add_f32 v[88:89], v[66:67], v[88:89]
	v_add_f32_e32 v64, v98, v64
	v_pk_mul_f32 v[100:101], v[88:89], v[88:89]
	v_add_f32_e32 v64, v99, v64
	v_add_f32_e32 v64, v100, v64
	v_add_f32_e32 v64, v101, v64
	ds_bpermute_b32 v65, v150, v64
	v_cvt_pk_bf16_f32 v66, v76, v77
	v_cvt_pk_bf16_f32 v67, v78, v79
	v_cvt_pk_bf16_f32 v68, v72, v73
	v_cvt_pk_bf16_f32 v69, v74, v75
	s_waitcnt lgkmcnt(0)
	v_add_f32_e32 v64, v64, v65
	ds_bpermute_b32 v65, v149, v64
	v_cvt_pk_bf16_f32 v70, v82, v83
	v_cvt_pk_bf16_f32 v71, v84, v85
	v_cvt_pk_bf16_f32 v72, v86, v87
	v_cvt_pk_bf16_f32 v73, v88, v89
	s_nop 1
	v_permlane16_swap_b32_e32 v66, v70
	v_permlane16_swap_b32_e32 v67, v71
	v_permlane16_swap_b32_e32 v68, v72
	v_permlane16_swap_b32_e32 v69, v73
	v_permlane32_swap_b32_e32 v66, v70
	v_permlane32_swap_b32_e32 v67, v71
	v_permlane32_swap_b32_e32 v68, v72
	v_permlane32_swap_b32_e32 v69, v73
	v_lshl_add_u64 v[238:239], v[90:91], 0, v[236:237]
	global_store_dwordx4 v[238:239], v[66:69], off
	global_store_dwordx4 v[238:239], v[70:73], off offset:64
	s_and_saveexec_b64 s[4:5], s[6:7]
	s_cbranch_execz .LBB0_1563
	s_waitcnt lgkmcnt(0)
	v_add_f32_e32 v66, v64, v65
	v_lshlrev_b64 v[64:65], 6, v[80:81]
	v_lshl_add_u64 v[64:65], s[14:15], 0, v[64:65]
	v_lshl_add_u64 v[64:65], s[26:27], 2, v[64:65]
	s_lshl_b32 s8, s40, 2
	v_lshl_add_u64 v[64:65], v[64:65], 0, s[8:9]
	global_store_dword v[64:65], v66, off
.LBB0_1563:
	s_or_b64 exec, exec, s[4:5]
	v_add_u32_e32 v64, 0x80, v140
	s_waitcnt lgkmcnt(0)
	v_ashrrev_i32_e32 v65, 31, v64
	v_lshlrev_b64 v[66:67], 11, v[64:65]
	v_lshl_add_u64 v[66:67], s[12:13], 0, v[66:67]
	v_lshl_add_u64 v[74:75], v[138:139], 1, v[66:67]
	global_load_dwordx4 v[66:69], v[74:75], off
	global_load_dwordx4 v[70:73], v[74:75], off offset:16
	s_waitcnt vmcnt(1)
	v_lshlrev_b32_e32 v76, 16, v66
	v_and_b32_e32 v77, 0xffff0000, v66
	v_lshlrev_b32_e32 v66, 16, v67
	v_and_b32_e32 v67, 0xffff0000, v67
	v_lshlrev_b32_e32 v78, 16, v68
	v_and_b32_e32 v79, 0xffff0000, v68
	v_lshlrev_b32_e32 v68, 16, v69
	v_and_b32_e32 v69, 0xffff0000, v69
	s_waitcnt vmcnt(0)
	v_lshlrev_b32_e32 v80, 16, v70
	v_and_b32_e32 v81, 0xffff0000, v70
	v_lshlrev_b32_e32 v70, 16, v71
	v_and_b32_e32 v71, 0xffff0000, v71
	v_lshlrev_b32_e32 v82, 16, v72
	v_and_b32_e32 v83, 0xffff0000, v72
	v_pk_add_f32 v[60:61], v[60:61], v[76:77]
	v_pk_add_f32 v[62:63], v[62:63], v[66:67]
	v_pk_add_f32 v[58:59], v[58:59], v[68:69]
	v_pk_add_f32 v[68:69], v[54:55], v[70:71]
	v_pk_add_f32 v[70:71], v[48:49], v[82:83]
	v_pk_mul_f32 v[48:49], v[60:61], v[60:61]
	v_pk_add_f32 v[66:67], v[52:53], v[80:81]
	v_pk_mul_f32 v[52:53], v[62:63], v[62:63]
	v_add_f32_e32 v48, v48, v49
	v_pk_add_f32 v[56:57], v[56:57], v[78:79]
	v_add_f32_e32 v48, v52, v48
	v_pk_mul_f32 v[54:55], v[56:57], v[56:57]
	v_add_f32_e32 v48, v53, v48
	v_add_f32_e32 v48, v54, v48
	v_pk_mul_f32 v[76:77], v[58:59], v[58:59]
	v_add_f32_e32 v48, v55, v48
	v_add_f32_e32 v48, v76, v48
	v_pk_mul_f32 v[78:79], v[66:67], v[66:67]
	v_add_f32_e32 v48, v77, v48
	v_add_f32_e32 v48, v78, v48
	v_pk_mul_f32 v[80:81], v[68:69], v[68:69]
	v_add_f32_e32 v48, v79, v48
	v_add_f32_e32 v48, v80, v48
	v_lshlrev_b32_e32 v72, 16, v73
	v_and_b32_e32 v73, 0xffff0000, v73
	v_pk_mul_f32 v[82:83], v[70:71], v[70:71]
	v_add_f32_e32 v48, v81, v48
	v_pk_add_f32 v[72:73], v[50:51], v[72:73]
	v_add_f32_e32 v48, v82, v48
	v_pk_mul_f32 v[84:85], v[72:73], v[72:73]
	v_add_f32_e32 v48, v83, v48
	v_add_f32_e32 v48, v84, v48
	v_add_f32_e32 v48, v85, v48
	ds_bpermute_b32 v49, v150, v48
	v_cvt_pk_bf16_f32 v50, v60, v61
	v_cvt_pk_bf16_f32 v51, v62, v63
	v_cvt_pk_bf16_f32 v52, v56, v57
	v_cvt_pk_bf16_f32 v53, v58, v59
	s_waitcnt lgkmcnt(0)
	v_add_f32_e32 v48, v48, v49
	ds_bpermute_b32 v49, v149, v48
	v_cvt_pk_bf16_f32 v54, v66, v67
	v_cvt_pk_bf16_f32 v55, v68, v69
	v_cvt_pk_bf16_f32 v56, v70, v71
	v_cvt_pk_bf16_f32 v57, v72, v73
	s_nop 1
	v_permlane16_swap_b32_e32 v50, v54
	v_permlane16_swap_b32_e32 v51, v55
	v_permlane16_swap_b32_e32 v52, v56
	v_permlane16_swap_b32_e32 v53, v57
	v_permlane32_swap_b32_e32 v50, v54
	v_permlane32_swap_b32_e32 v51, v55
	v_permlane32_swap_b32_e32 v52, v56
	v_permlane32_swap_b32_e32 v53, v57
	v_lshl_add_u64 v[238:239], v[74:75], 0, v[236:237]
	global_store_dwordx4 v[238:239], v[50:53], off
	global_store_dwordx4 v[238:239], v[54:57], off offset:64
	s_and_saveexec_b64 s[4:5], s[6:7]
	s_cbranch_execz .LBB0_1565
	s_waitcnt lgkmcnt(0)
	v_add_f32_e32 v50, v48, v49
	v_lshlrev_b64 v[48:49], 6, v[64:65]
	v_lshl_add_u64 v[48:49], s[14:15], 0, v[48:49]
	v_lshl_add_u64 v[48:49], s[26:27], 2, v[48:49]
	s_lshl_b32 s8, s40, 2
	v_lshl_add_u64 v[48:49], v[48:49], 0, s[8:9]
	global_store_dword v[48:49], v50, off
.LBB0_1565:
	s_or_b64 exec, exec, s[4:5]
	v_add_u32_e32 v48, 0x90, v140
	s_waitcnt lgkmcnt(0)
	v_ashrrev_i32_e32 v49, 31, v48
	v_lshlrev_b64 v[50:51], 11, v[48:49]
	v_lshl_add_u64 v[50:51], s[12:13], 0, v[50:51]
	v_lshl_add_u64 v[58:59], v[138:139], 1, v[50:51]
	global_load_dwordx4 v[50:53], v[58:59], off
	global_load_dwordx4 v[54:57], v[58:59], off offset:16
	s_waitcnt vmcnt(1)
	v_lshlrev_b32_e32 v60, 16, v50
	v_and_b32_e32 v61, 0xffff0000, v50
	v_lshlrev_b32_e32 v50, 16, v51
	v_and_b32_e32 v51, 0xffff0000, v51
	v_lshlrev_b32_e32 v62, 16, v52
	v_and_b32_e32 v63, 0xffff0000, v52
	v_lshlrev_b32_e32 v52, 16, v53
	v_and_b32_e32 v53, 0xffff0000, v53
	s_waitcnt vmcnt(0)
	v_lshlrev_b32_e32 v64, 16, v54
	v_and_b32_e32 v65, 0xffff0000, v54
	v_lshlrev_b32_e32 v54, 16, v55
	v_and_b32_e32 v55, 0xffff0000, v55
	v_lshlrev_b32_e32 v66, 16, v56
	v_and_b32_e32 v67, 0xffff0000, v56
	v_pk_add_f32 v[44:45], v[44:45], v[60:61]
	v_pk_add_f32 v[46:47], v[46:47], v[50:51]
	v_pk_add_f32 v[42:43], v[42:43], v[52:53]
	v_pk_add_f32 v[52:53], v[38:39], v[54:55]
	v_pk_add_f32 v[54:55], v[32:33], v[66:67]
	v_pk_mul_f32 v[32:33], v[44:45], v[44:45]
	v_pk_add_f32 v[50:51], v[36:37], v[64:65]
	v_pk_mul_f32 v[36:37], v[46:47], v[46:47]
	v_add_f32_e32 v32, v32, v33
	v_pk_add_f32 v[40:41], v[40:41], v[62:63]
	v_add_f32_e32 v32, v36, v32
	v_pk_mul_f32 v[38:39], v[40:41], v[40:41]
	v_add_f32_e32 v32, v37, v32
	v_add_f32_e32 v32, v38, v32
	v_pk_mul_f32 v[60:61], v[42:43], v[42:43]
	v_add_f32_e32 v32, v39, v32
	v_add_f32_e32 v32, v60, v32
	v_pk_mul_f32 v[62:63], v[50:51], v[50:51]
	v_add_f32_e32 v32, v61, v32
	v_add_f32_e32 v32, v62, v32
	v_pk_mul_f32 v[64:65], v[52:53], v[52:53]
	v_add_f32_e32 v32, v63, v32
	v_add_f32_e32 v32, v64, v32
	v_lshlrev_b32_e32 v56, 16, v57
	v_and_b32_e32 v57, 0xffff0000, v57
	v_pk_mul_f32 v[66:67], v[54:55], v[54:55]
	v_add_f32_e32 v32, v65, v32
	v_pk_add_f32 v[56:57], v[34:35], v[56:57]
	v_add_f32_e32 v32, v66, v32
	v_pk_mul_f32 v[68:69], v[56:57], v[56:57]
	v_add_f32_e32 v32, v67, v32
	v_add_f32_e32 v32, v68, v32
	v_add_f32_e32 v32, v69, v32
	ds_bpermute_b32 v33, v150, v32
	v_cvt_pk_bf16_f32 v34, v44, v45
	v_cvt_pk_bf16_f32 v35, v46, v47
	v_cvt_pk_bf16_f32 v36, v40, v41
	v_cvt_pk_bf16_f32 v37, v42, v43
	s_waitcnt lgkmcnt(0)
	v_add_f32_e32 v32, v32, v33
	ds_bpermute_b32 v33, v149, v32
	v_cvt_pk_bf16_f32 v38, v50, v51
	v_cvt_pk_bf16_f32 v39, v52, v53
	v_cvt_pk_bf16_f32 v40, v54, v55
	v_cvt_pk_bf16_f32 v41, v56, v57
	s_nop 1
	v_permlane16_swap_b32_e32 v34, v38
	v_permlane16_swap_b32_e32 v35, v39
	v_permlane16_swap_b32_e32 v36, v40
	v_permlane16_swap_b32_e32 v37, v41
	v_permlane32_swap_b32_e32 v34, v38
	v_permlane32_swap_b32_e32 v35, v39
	v_permlane32_swap_b32_e32 v36, v40
	v_permlane32_swap_b32_e32 v37, v41
	v_lshl_add_u64 v[238:239], v[58:59], 0, v[236:237]
	global_store_dwordx4 v[238:239], v[34:37], off
	global_store_dwordx4 v[238:239], v[38:41], off offset:64
	s_and_saveexec_b64 s[4:5], s[6:7]
	s_cbranch_execz .LBB0_1567
	s_waitcnt lgkmcnt(0)
	v_add_f32_e32 v34, v32, v33
	v_lshlrev_b64 v[32:33], 6, v[48:49]
	v_lshl_add_u64 v[32:33], s[14:15], 0, v[32:33]
	v_lshl_add_u64 v[32:33], s[26:27], 2, v[32:33]
	s_lshl_b32 s8, s40, 2
	v_lshl_add_u64 v[32:33], v[32:33], 0, s[8:9]
	global_store_dword v[32:33], v34, off
.LBB0_1567:
	s_or_b64 exec, exec, s[4:5]
	v_add_u32_e32 v32, 0xa0, v140
	s_waitcnt lgkmcnt(0)
	v_ashrrev_i32_e32 v33, 31, v32
	v_lshlrev_b64 v[34:35], 11, v[32:33]
	v_lshl_add_u64 v[34:35], s[12:13], 0, v[34:35]
	v_lshl_add_u64 v[42:43], v[138:139], 1, v[34:35]
	global_load_dwordx4 v[34:37], v[42:43], off
	global_load_dwordx4 v[38:41], v[42:43], off offset:16
	s_waitcnt vmcnt(1)
	v_lshlrev_b32_e32 v44, 16, v34
	v_and_b32_e32 v45, 0xffff0000, v34
	v_lshlrev_b32_e32 v34, 16, v35
	v_and_b32_e32 v35, 0xffff0000, v35
	v_lshlrev_b32_e32 v46, 16, v36
	v_and_b32_e32 v47, 0xffff0000, v36
	v_lshlrev_b32_e32 v36, 16, v37
	v_and_b32_e32 v37, 0xffff0000, v37
	s_waitcnt vmcnt(0)
	v_lshlrev_b32_e32 v48, 16, v38
	v_and_b32_e32 v49, 0xffff0000, v38
	v_lshlrev_b32_e32 v38, 16, v39
	v_and_b32_e32 v39, 0xffff0000, v39
	v_lshlrev_b32_e32 v50, 16, v40
	v_and_b32_e32 v51, 0xffff0000, v40
	v_pk_add_f32 v[28:29], v[28:29], v[44:45]
	v_pk_add_f32 v[30:31], v[30:31], v[34:35]
	v_pk_add_f32 v[26:27], v[26:27], v[36:37]
	v_pk_add_f32 v[36:37], v[22:23], v[38:39]
	v_pk_add_f32 v[38:39], v[16:17], v[50:51]
	v_pk_mul_f32 v[16:17], v[28:29], v[28:29]
	v_pk_add_f32 v[34:35], v[20:21], v[48:49]
	v_pk_mul_f32 v[20:21], v[30:31], v[30:31]
	v_add_f32_e32 v16, v16, v17
	v_pk_add_f32 v[24:25], v[24:25], v[46:47]
	v_add_f32_e32 v16, v20, v16
	v_pk_mul_f32 v[22:23], v[24:25], v[24:25]
	v_add_f32_e32 v16, v21, v16
	v_add_f32_e32 v16, v22, v16
	v_pk_mul_f32 v[44:45], v[26:27], v[26:27]
	v_add_f32_e32 v16, v23, v16
	v_add_f32_e32 v16, v44, v16
	v_pk_mul_f32 v[46:47], v[34:35], v[34:35]
	v_add_f32_e32 v16, v45, v16
	v_add_f32_e32 v16, v46, v16
	v_pk_mul_f32 v[48:49], v[36:37], v[36:37]
	v_add_f32_e32 v16, v47, v16
	v_add_f32_e32 v16, v48, v16
	v_lshlrev_b32_e32 v40, 16, v41
	v_and_b32_e32 v41, 0xffff0000, v41
	v_pk_mul_f32 v[50:51], v[38:39], v[38:39]
	v_add_f32_e32 v16, v49, v16
	v_pk_add_f32 v[40:41], v[18:19], v[40:41]
	v_add_f32_e32 v16, v50, v16
	v_pk_mul_f32 v[52:53], v[40:41], v[40:41]
	v_add_f32_e32 v16, v51, v16
	v_add_f32_e32 v16, v52, v16
	v_add_f32_e32 v16, v53, v16
	ds_bpermute_b32 v17, v150, v16
	v_cvt_pk_bf16_f32 v18, v28, v29
	v_cvt_pk_bf16_f32 v19, v30, v31
	v_cvt_pk_bf16_f32 v20, v24, v25
	v_cvt_pk_bf16_f32 v21, v26, v27
	s_waitcnt lgkmcnt(0)
	v_add_f32_e32 v16, v16, v17
	ds_bpermute_b32 v17, v149, v16
	v_cvt_pk_bf16_f32 v22, v34, v35
	v_cvt_pk_bf16_f32 v23, v36, v37
	v_cvt_pk_bf16_f32 v24, v38, v39
	v_cvt_pk_bf16_f32 v25, v40, v41
	s_nop 1
	v_permlane16_swap_b32_e32 v18, v22
	v_permlane16_swap_b32_e32 v19, v23
	v_permlane16_swap_b32_e32 v20, v24
	v_permlane16_swap_b32_e32 v21, v25
	v_permlane32_swap_b32_e32 v18, v22
	v_permlane32_swap_b32_e32 v19, v23
	v_permlane32_swap_b32_e32 v20, v24
	v_permlane32_swap_b32_e32 v21, v25
	v_lshl_add_u64 v[238:239], v[42:43], 0, v[236:237]
	global_store_dwordx4 v[238:239], v[18:21], off
	global_store_dwordx4 v[238:239], v[22:25], off offset:64
	s_and_saveexec_b64 s[4:5], s[6:7]
	s_cbranch_execz .LBB0_1569
	s_waitcnt lgkmcnt(0)
	v_add_f32_e32 v18, v16, v17
	v_lshlrev_b64 v[16:17], 6, v[32:33]
	v_lshl_add_u64 v[16:17], s[14:15], 0, v[16:17]
	v_lshl_add_u64 v[16:17], s[26:27], 2, v[16:17]
	s_lshl_b32 s8, s40, 2
	v_lshl_add_u64 v[16:17], v[16:17], 0, s[8:9]
	global_store_dword v[16:17], v18, off
.LBB0_1569:
	s_or_b64 exec, exec, s[4:5]
	v_add_u32_e32 v16, 0xb0, v140
	s_waitcnt lgkmcnt(0)
	v_ashrrev_i32_e32 v17, 31, v16
	v_lshlrev_b64 v[18:19], 11, v[16:17]
	v_lshl_add_u64 v[18:19], s[12:13], 0, v[18:19]
	v_lshl_add_u64 v[26:27], v[138:139], 1, v[18:19]
	global_load_dwordx4 v[18:21], v[26:27], off
	global_load_dwordx4 v[22:25], v[26:27], off offset:16
	s_waitcnt vmcnt(1)
	v_lshlrev_b32_e32 v28, 16, v18
	v_and_b32_e32 v29, 0xffff0000, v18
	v_lshlrev_b32_e32 v18, 16, v19
	v_and_b32_e32 v19, 0xffff0000, v19
	v_lshlrev_b32_e32 v30, 16, v20
	v_and_b32_e32 v31, 0xffff0000, v20
	v_lshlrev_b32_e32 v20, 16, v21
	v_and_b32_e32 v21, 0xffff0000, v21
	s_waitcnt vmcnt(0)
	v_lshlrev_b32_e32 v32, 16, v22
	v_and_b32_e32 v33, 0xffff0000, v22
	v_lshlrev_b32_e32 v22, 16, v23
	v_and_b32_e32 v23, 0xffff0000, v23
	v_lshlrev_b32_e32 v34, 16, v24
	v_and_b32_e32 v35, 0xffff0000, v24
	v_pk_add_f32 v[12:13], v[12:13], v[28:29]
	v_pk_add_f32 v[14:15], v[14:15], v[18:19]
	v_pk_add_f32 v[10:11], v[10:11], v[20:21]
	v_pk_add_f32 v[20:21], v[6:7], v[22:23]
	v_pk_add_f32 v[22:23], v[0:1], v[34:35]
	v_pk_mul_f32 v[0:1], v[12:13], v[12:13]
	v_pk_add_f32 v[18:19], v[4:5], v[32:33]
	v_pk_mul_f32 v[4:5], v[14:15], v[14:15]
	v_add_f32_e32 v0, v0, v1
	v_pk_add_f32 v[8:9], v[8:9], v[30:31]
	v_add_f32_e32 v0, v4, v0
	v_pk_mul_f32 v[6:7], v[8:9], v[8:9]
	v_add_f32_e32 v0, v5, v0
	v_add_f32_e32 v0, v6, v0
	v_pk_mul_f32 v[28:29], v[10:11], v[10:11]
	v_add_f32_e32 v0, v7, v0
	v_add_f32_e32 v0, v28, v0
	v_pk_mul_f32 v[30:31], v[18:19], v[18:19]
	v_add_f32_e32 v0, v29, v0
	v_add_f32_e32 v0, v30, v0
	v_pk_mul_f32 v[32:33], v[20:21], v[20:21]
	v_add_f32_e32 v0, v31, v0
	v_add_f32_e32 v0, v32, v0
	v_lshlrev_b32_e32 v24, 16, v25
	v_and_b32_e32 v25, 0xffff0000, v25
	v_pk_mul_f32 v[34:35], v[22:23], v[22:23]
	v_add_f32_e32 v0, v33, v0
	v_pk_add_f32 v[24:25], v[2:3], v[24:25]
	v_add_f32_e32 v0, v34, v0
	v_pk_mul_f32 v[36:37], v[24:25], v[24:25]
	v_add_f32_e32 v0, v35, v0
	v_add_f32_e32 v0, v36, v0
	v_add_f32_e32 v0, v37, v0
	ds_bpermute_b32 v1, v150, v0
	v_cvt_pk_bf16_f32 v2, v12, v13
	v_cvt_pk_bf16_f32 v3, v14, v15
	v_cvt_pk_bf16_f32 v4, v8, v9
	v_cvt_pk_bf16_f32 v5, v10, v11
	s_waitcnt lgkmcnt(0)
	v_add_f32_e32 v0, v0, v1
	ds_bpermute_b32 v1, v149, v0
	v_cvt_pk_bf16_f32 v6, v18, v19
	v_cvt_pk_bf16_f32 v7, v20, v21
	v_cvt_pk_bf16_f32 v8, v22, v23
	v_cvt_pk_bf16_f32 v9, v24, v25
	s_nop 1
	v_permlane16_swap_b32_e32 v2, v6
	v_permlane16_swap_b32_e32 v3, v7
	v_permlane16_swap_b32_e32 v4, v8
	v_permlane16_swap_b32_e32 v5, v9
	v_permlane32_swap_b32_e32 v2, v6
	v_permlane32_swap_b32_e32 v3, v7
	v_permlane32_swap_b32_e32 v4, v8
	v_permlane32_swap_b32_e32 v5, v9
	v_lshl_add_u64 v[238:239], v[26:27], 0, v[236:237]
	global_store_dwordx4 v[238:239], v[2:5], off
	global_store_dwordx4 v[238:239], v[6:9], off offset:64
	s_and_saveexec_b64 s[4:5], s[6:7]
	s_cbranch_execz .LBB0_1571
	s_waitcnt lgkmcnt(0)
	v_add_f32_e32 v2, v0, v1
	v_lshlrev_b64 v[0:1], 6, v[16:17]
	v_lshl_add_u64 v[0:1], s[14:15], 0, v[0:1]
	v_lshl_add_u64 v[0:1], s[26:27], 2, v[0:1]
	s_lshl_b32 s8, s40, 2
	v_lshl_add_u64 v[0:1], v[0:1], 0, s[8:9]
	global_store_dword v[0:1], v2, off
